# in-proj main GEMM: every other workgroup of an XCD starts the phase ~5us late (desynchronises the epilogue store bursts)
# speedup vs baseline: 1.0043x; 1.0043x over previous
.LBB0_689:
	v_readlane_b32 s2, v254, 36
	v_readlane_b32 s3, v254, 37
	s_mov_b32 s10, s2
	s_lshl_b32 s2, s2, 1
	s_ashr_i32 s3, s2, 31
	s_lshl_b64 s[2:3], s[2:3], 18
	s_waitcnt lgkmcnt(0)
	s_add_u32 s5, s78, s2
	s_addc_u32 s6, s79, s3
	v_readlane_b32 s2, v254, 38
	v_readlane_b32 s3, v254, 39
	s_lshl_b64 s[2:3], s[2:3], 3
	s_add_u32 s2, s5, s2
	s_addc_u32 s3, s6, s3
	s_ashr_i32 s11, s10, 31
	s_load_dword s8, s[84:85], 0x0
	s_lshl_b64 s[6:7], s[10:11], 24
	s_add_u32 s5, s78, s6
	s_addc_u32 s6, s79, s7
	s_add_u32 s11, s5, 0x200000
	s_addc_u32 s12, s6, 0
	s_andn2_b64 vcc, exec, s[0:1]
	s_cbranch_vccnz .LBB0_769
	v_ashrrev_i32_e32 v0, 31, v10
	v_lshrrev_b32_e32 v0, 26, v0
	v_add_u32_e32 v0, v10, v0
	v_ashrrev_i32_e32 v11, 6, v0
	v_bfe_i32 v0, v10, 27, 1
	v_lshlrev_b32_e32 v2, 4, v10
	v_lshrrev_b32_e32 v0, 22, v0
	v_add_u32_e32 v0, v2, v0
	v_and_b32_e32 v0, 0xfffffc00, v0
	v_sub_u32_e32 v0, v2, v0
	v_lshrrev_b32_e32 v3, 4, v0
	v_bitop3_b32 v3, v3, v0, 32 bitop3:0x6c
	v_ashrrev_i32_e32 v0, 31, v0
	v_lshrrev_b32_e32 v0, 26, v0
	v_add_u32_e32 v0, v3, v0
	v_ashrrev_i32_e32 v12, 6, v0
	v_lshlrev_b32_e32 v4, 3, v11
	v_mul_i32_i24_e32 v5, 64, v12
	v_and_b32_e32 v4, -16, v4
	v_sub_u32_e32 v3, v3, v5
	v_add_u32_e32 v0, v12, v4
	v_ashrrev_i16_sdwa v3, v209, sext(v3) dst_sel:DWORD dst_unused:UNUSED_PAD src0_sel:DWORD src1_sel:BYTE_0
	v_lshlrev_b32_e32 v4, 5, v11
	v_bfe_i32 v13, v3, 0, 16
	v_lshlrev_b32_e32 v3, 1, v0
	v_lshrrev_b32_e32 v5, 2, v0
	v_and_b32_e32 v6, 3, v12
	v_and_b32_e32 v4, 32, v4
	v_and_b32_e32 v3, 24, v3
	v_and_b32_e32 v5, 4, v5
	v_and_or_b32 v6, v0, s76, v6
	v_or3_b32 v3, v6, v5, v3
	v_add_lshl_u32 v4, v4, v13, 1
	v_add_u32_e32 v2, 0x2000, v2
	v_lshl_add_u32 v130, v0, 11, v4
	v_lshl_add_u32 v0, v3, 11, v4
	v_ashrrev_i32_e32 v3, 31, v2
	v_lshrrev_b32_e32 v3, 22, v3
	v_add_u32_e32 v3, v2, v3
	v_ashrrev_i32_e32 v14, 10, v3
	v_mul_i32_i24_e32 v3, 0x400, v14
	v_sub_u32_e32 v2, v2, v3
	v_lshrrev_b32_e32 v3, 4, v2
	v_bitop3_b32 v2, v3, v2, 32 bitop3:0x6c
	v_ashrrev_i32_e32 v4, 31, v2
	v_lshrrev_b32_e32 v4, 26, v4
	v_add_u32_e32 v4, v2, v4
	v_lshlrev_b32_e32 v3, 3, v14
	v_ashrrev_i32_e32 v15, 6, v4
	v_and_b32_e32 v4, 0xc0, v4
	s_ashr_i32 s19, s4, 6
	s_ashr_i32 s55, s54, 31
	s_ashr_i32 s43, s42, 31
	s_ashr_i32 s5, s4, 8
	v_and_b32_e32 v3, -16, v3
	v_sub_u32_e32 v2, v2, v4
	s_lshl_b32 s10, s19, 10
	s_lshl_b64 s[6:7], s[54:55], 19
	s_lshl_b64 s[0:1], s[42:43], 19
	v_add_u32_e32 v3, v15, v3
	v_ashrrev_i16_sdwa v2, v209, sext(v2) dst_sel:DWORD dst_unused:UNUSED_PAD src0_sel:DWORD src1_sel:BYTE_0
	s_add_u32 s0, s11, s0
	v_lshlrev_b32_e32 v5, 5, v14
	v_bfe_i32 v16, v2, 0, 16
	v_lshlrev_b32_e32 v2, 1, v3
	v_lshrrev_b32_e32 v4, 2, v3
	v_and_b32_e32 v6, 3, v15
	s_addc_u32 s1, s12, s1
	s_add_i32 s13, s10, 0
	v_and_b32_e32 v5, 32, v5
	v_and_b32_e32 v2, 24, v2
	v_and_b32_e32 v4, 4, v4
	v_and_or_b32 v6, v3, s76, v6
	s_bitcmp1_b32 s51, 3
	s_cbranch_scc0 .Lstag_inproj
	s_sleep 127
.Lstag_inproj:
	s_add_i32 m0, s13, 0x10000
	v_or3_b32 v2, v6, v4, v2
	v_add_lshl_u32 v4, v5, v16, 1
	global_load_lds_dwordx4 v0, s[0:1]
	s_add_i32 m0, s13, 0x12000
	v_lshl_add_u32 v134, v2, 11, v4
	s_add_u32 s14, s0, 0x40000
	global_load_lds_dwordx4 v134, s[0:1]
	s_addc_u32 s15, s1, 0
	s_add_i32 m0, s13, 0x14000
	v_lshl_add_u32 v132, v3, 11, v4
	global_load_lds_dwordx4 v0, s[14:15]
	s_add_i32 m0, s13, 0x16000
	v_mov_b32_e32 v135, v1
	global_load_lds_dwordx4 v134, s[14:15]
	v_readlane_b32 s14, v254, 43
	v_readlane_b32 s15, v254, 44
	s_add_u32 s6, s14, s6
	s_addc_u32 s7, s15, s7
	s_add_i32 s14, s13, 0x2000
	s_mov_b32 m0, s13
	s_add_u32 s20, s6, 0x40000
	global_load_lds_dwordx4 v130, s[6:7]
	s_mov_b32 m0, s14
	s_addc_u32 s21, s7, 0
	s_add_i32 s15, s13, 0x4000
	global_load_lds_dwordx4 v132, s[6:7]
	s_mov_b32 m0, s15
	s_add_i32 s16, s13, 0x6000
	global_load_lds_dwordx4 v130, s[20:21]
	s_mov_b32 m0, s16
	v_mov_b32_e32 v131, v1
	global_load_lds_dwordx4 v132, s[20:21]
	v_mov_b32_e32 v133, v1
	s_cmp_eq_u32 s5, 1
	v_lshl_add_u64 v[8:9], s[0:1], 0, v[0:1]
	v_lshl_add_u64 v[6:7], s[0:1], 0, v[134:135]
	v_lshl_add_u64 v[2:3], s[6:7], 0, v[130:131]
	s_cselect_b64 s[26:27], -1, 0
	s_cmp_lg_u32 s5, 1
	v_lshl_add_u64 v[4:5], s[6:7], 0, v[132:133]
	s_cbranch_scc1 .LBB0_692
	s_barrier
